# GEMM phases: one static s_setprio 1 for waves 0-3 for the whole phase (the other physical half than the previous variant)
# baseline (speedup 1.0000x reference)
; template <class Epi, class Sched>
; __device__ __forceinline__ void gemm_phase(PG8_LAS unsigned char* lds, const Gemm g, const Sched& S, const Epi& E) {
;     int tid_ = threadIdx.x; asm volatile("" : "+v"(tid_));
;     const int tid = tid_, wid = __builtin_amdgcn_readfirstlane(tid >> 6), lane = tid & 63, wr = wid >> 2, wc = wid & 3, fr = lane & 15, fq = lane >> 4;
.LBB0_159:
	s_or_b64 exec, exec, s[0:1]
	v_readfirstlane_b32 s98, v244
	s_nop 3
	s_lshr_b32 s98, s98, 6
	s_cmp_ge_u32 s98, 4
	s_cbranch_scc1 .Lgprio_0
	s_setprio 1
